# v42 + attention loop VALU trims: add-zero removed, one copy less in each row-max finish (3 VALU per two tile-steps)
# speedup vs baseline: 1.0008x; 1.0008x over previous
; #define SB() __builtin_amdgcn_sched_barrier(0)
; #define MF32(a,b,c) __builtin_amdgcn_mfma_f32_32x32x16_bf16(a,b,c,0,0,0)
; #define EXP1(x) x=__builtin_amdgcn_exp2f((x)-mh_)
; __device__ __forceinline__ bf16x8 vfrag(lds_cptr vp,int i){ const s16x4 lo=vtr(vp+(i&3)*4096+(i>>2)*1024), hh=vtr(vp+(i&3)*4096+(i>>2)*1024+512); return (bf16x8){lo[0],lo[1],lo[2],lo[3],hh[0],hh[1],hh[2],hh[3]}; }
; __device__ __forceinline__ u32x4 packw(const f32x16&p,int base){ u32x4 w; w[0]=cvtpk_s(p[base],p[base+1]); w[1]=cvtpk_s(p[base+2],p[base+3]); w[2]=cvtpk_s(p[base+4],p[base+5]); w[3]=cvtpk_s(p[base+6],p[base+7]); return w; }
;   #define KF(i) LDSQ(kpn+((i)>>1)*2048+((i)&1)*512)
;   #define QF(d0) LDSQ(qp+(d0)*1024)
; template<int THRL,bool FIRST> __device__ __forceinline__ void step_main(f32x16&p0,f32x16&p1,f32x16&n0,f32x16&n1,St&S,lds_cptr kpn,lds_cptr qp,lds_cptr vp,float*wsf,int r32,int hi,float&rm){
;     ...
;   bf16x8 ka=KF(0),kb=KF(1),kc=KF(2),kd=KF(3),qa=QF(0),qb=QF(1);
;   decide<THRL,FIRST>(rm,S,wsf,r32,hi);
;   u32x4 pw0,pw1,pw2,pw3; const float mh_=S.mhat; const f32x16 z=f32x16{};
;   SB();
;   n0=MF32(ka,qa,z); ka=KF(4); EXP1(p0[0]);EXP1(p0[1]);EXP1(p0[2]); SB();
;   n1=MF32(kb,qa,z); kb=KF(5); qa=QF(2); EXP1(p0[3]);EXP1(p0[4]);EXP1(p0[5]); SB();
;   n0=MF32(kc,qb,n0);   kc=KF(6); EXP1(p0[6]);EXP1(p0[7]);EXP1(p0[8]); SB();
;   n1=MF32(kd,qb,n1);   kd=KF(7); qb=QF(3); EXP1(p0[9]);EXP1(p0[10]);EXP1(p0[11]); SB();
;   bf16x8 vfa=vfrag(vp,0);
;   n0=MF32(ka,qa,n0);   EXP1(p0[12]);EXP1(p0[13]);EXP1(p0[14]); pw0=packw(p0,0); SB();
;   bf16x8 vfb=vfrag(vp,1);
;   n1=MF32(kb,qa,n1);   EXP1(p0[15]);EXP1(p1[0]);EXP1(p1[1]); SB();
;   bf16x8 vfc=vfrag(vp,2);
;   n0=MF32(kc,qb,n0);   EXP1(p1[2]);EXP1(p1[3]);EXP1(p1[4]); pw1=packw(p0,8); SB();
;   bf16x8 vfd=vfrag(vp,3);
;   n1=MF32(kd,qb,n1);   EXP1(p1[5]);EXP1(p1[6]);EXP1(p1[7]); SB();
;     ...
;   float sa=p0[0]+p0[1];
;     ...
;   PVG(0,pw0,vfa,4, p0[2],p0[3],p0[4],p0[5],   do{EXP1(p1[8]);EXP1(p1[9]);}while(0));
;   PVG(1,pw0,vfb,5, p0[6],p0[7],p0[8],p0[9], do{EXP1(p1[10]);EXP1(p1[11]);}while(0));
;   PVG(2,pw0,vfc,6, p0[10],p0[11],p0[12],p0[13], do{EXP1(p1[12]);EXP1(p1[13]);}while(0));
;   PVG(3,pw0,vfd,7, p0[14],p0[15],p1[0],p1[1],   do{EXP1(p1[14]);EXP1(p1[15]);}while(0));
;   PVG(4,pw1,vfa,8, p1[2],p1[3],p1[4],p1[5],   pw2=packw(p1,0));
;   PVG(5,pw1,vfb,9, p1[6],p1[7],p1[8],p1[9], pw3=packw(p1,8));
.LBB0_277:
	s_add_i32 s4, s91, 0x2000
	s_cmpk_lg_i32 s91, 0x4000
	s_cselect_b32 s88, s4, 0
	s_add_i32 s90, s90, 2
	v_mfma_f32_32x32x16_bf16 v[98:113], v[204:207], v[164:167], v[146:161]
	s_add_i32 s4, s88, s84
	s_add_u32 s60, s58, 0xc0000
	s_addc_u32 s61, s59, 0
	s_mov_b32 s5, m0
	s_mov_b32 m0, s4
	s_nop 0
	global_load_lds_dwordx4 v252, s[60:61]
	s_mov_b32 m0, s5
	v_exp_f32_e32 v130, v130
	v_exp_f32_e32 v131, v131
	v_exp_f32_e32 v132, v132
	v_exp_f32_e32 v133, v133
	v_exp_f32_e32 v134, v134
	v_exp_f32_e32 v135, v135
	v_mfma_f32_32x32x16_bf16 v[82:97], v[208:211], v[164:167], v[146:161]
	s_add_u32 s60, s50, 0xc0000
	s_addc_u32 s61, s51, 0
	s_mov_b32 s4, m0
	s_mov_b32 m0, s80
	s_nop 0
	global_load_lds_dwordx4 v250, s[60:61]
	s_mov_b32 m0, s4
	v_mfma_f32_32x32x16_bf16 v[98:113], v[212:215], v[168:171], v[98:113]
	s_add_u32 s60, s50, 0xc0080
	s_addc_u32 s61, s51, 0
	s_mov_b32 s4, m0
	s_mov_b32 m0, s83
	s_nop 0
	global_load_lds_dwordx4 v250, s[60:61]
	s_mov_b32 m0, s4
	v_exp_f32_e32 v136, v136
	v_exp_f32_e32 v137, v137
	v_exp_f32_e32 v138, v138
	v_mfma_f32_32x32x16_bf16 v[82:97], v[216:219], v[168:171], v[82:97]
	v_exp_f32_e32 v139, v139
	v_exp_f32_e32 v140, v140
	v_exp_f32_e32 v141, v141
	v_mfma_f32_32x32x16_bf16 v[98:113], v[220:223], v[172:175], v[98:113]
	v_exp_f32_e32 v142, v142
	ds_read_b64_tr_b16 v[4:5], v246 offset:40960
	ds_read_b64_tr_b16 v[6:7], v246 offset:41472
	v_exp_f32_e32 v143, v143
	v_exp_f32_e32 v144, v144
	v_cvt_pk_bf16_f32 v8, v130, v131
	v_cvt_pk_bf16_f32 v9, v132, v133
	v_cvt_pk_bf16_f32 v10, v134, v135
	v_cvt_pk_bf16_f32 v11, v136, v137
	v_mfma_f32_32x32x16_bf16 v[82:97], v[224:227], v[172:175], v[82:97]
	ds_read_b64_tr_b16 v[178:179], v246 offset:45056
	ds_read_b64_tr_b16 v[180:181], v246 offset:45568
	v_exp_f32_e32 v145, v145
	v_exp_f32_e32 v114, v114
	v_exp_f32_e32 v115, v115
	v_mfma_f32_32x32x16_bf16 v[98:113], v[228:231], v[236:239], v[98:113]
	ds_read_b64_tr_b16 v[182:183], v246 offset:49152
	ds_read_b64_tr_b16 v[184:185], v246 offset:49664
	v_exp_f32_e32 v116, v116
	v_exp_f32_e32 v117, v117
	v_exp_f32_e32 v118, v118
	v_cvt_pk_bf16_f32 v186, v138, v139
	v_cvt_pk_bf16_f32 v187, v140, v141
	v_cvt_pk_bf16_f32 v188, v142, v143
	v_cvt_pk_bf16_f32 v189, v144, v145
	v_mfma_f32_32x32x16_bf16 v[82:97], v[232:235], v[236:239], v[82:97]
	v_add_u32_e32 v240, s91, v249
	ds_read_b64_tr_b16 v[190:191], v246 offset:53248
	ds_read_b64_tr_b16 v[192:193], v246 offset:53760
	v_exp_f32_e32 v119, v119
	v_exp_f32_e32 v120, v120
	v_exp_f32_e32 v121, v121
	s_waitcnt lgkmcnt(6)
	v_mfma_f32_32x32x16_bf16 v[18:33], v[8:11], v[4:7], v[18:33]
	ds_read_b64_tr_b16 v[12:13], v246 offset:41984
	ds_read_b64_tr_b16 v[14:15], v246 offset:42496
	ds_read_b128 v[204:207], v240
	v_add_f32_e32 v194, v130, v131
	v_exp_f32_e32 v122, v122
	v_exp_f32_e32 v123, v123
	v_add_f32_e32 v194, v132, v194
	v_add_f32_e32 v4, v133, v194
	v_add_f32_e32 v4, v134, v4
	v_add_f32_e32 v194, v135, v4
	s_waitcnt lgkmcnt(7)
	v_mfma_f32_32x32x16_bf16 v[34:49], v[8:11], v[178:181], v[34:49]
	ds_read_b64_tr_b16 v[4:5], v246 offset:46080
	ds_read_b64_tr_b16 v[6:7], v246 offset:46592
	ds_read_b128 v[208:211], v240 offset:512
	v_exp_f32_e32 v124, v124
	v_exp_f32_e32 v125, v125
	v_add_f32_e32 v194, v136, v194
	v_add_f32_e32 v178, v137, v194
	v_add_f32_e32 v178, v138, v178
	v_add_f32_e32 v194, v139, v178
	s_waitcnt lgkmcnt(8)
	v_mfma_f32_32x32x16_bf16 v[50:65], v[8:11], v[182:185], v[50:65]
	ds_read_b64_tr_b16 v[178:179], v246 offset:50176
	ds_read_b64_tr_b16 v[180:181], v246 offset:50688
	ds_read_b128 v[212:215], v240 offset:2048
	v_exp_f32_e32 v126, v126
	v_exp_f32_e32 v127, v127
	v_add_f32_e32 v194, v140, v194
	v_add_f32_e32 v182, v141, v194
	v_add_f32_e32 v182, v142, v182
	v_add_f32_e32 v194, v143, v182
	s_waitcnt lgkmcnt(9)
	v_mfma_f32_32x32x16_bf16 v[66:81], v[8:11], v[190:193], v[66:81]
	ds_read_b64_tr_b16 v[182:183], v246 offset:54272
	ds_read_b64_tr_b16 v[184:185], v246 offset:54784
	ds_read_b128 v[216:219], v240 offset:2560
	v_exp_f32_e32 v128, v128
	v_exp_f32_e32 v129, v129
	v_add_f32_e32 v194, v144, v194
	v_add_f32_e32 v8, v145, v194
	v_add_f32_e32 v8, v114, v8
	v_add_f32_e32 v190, v115, v8
	s_waitcnt lgkmcnt(10)
	v_mfma_f32_32x32x16_bf16 v[18:33], v[186:189], v[12:15], v[18:33]
	ds_read_b64_tr_b16 v[8:9], v246 offset:43008
	ds_read_b64_tr_b16 v[10:11], v246 offset:43520
	ds_read_b128 v[220:223], v240 offset:4096
	v_add_f32_e32 v190, v116, v190
	v_add_f32_e32 v190, v117, v190
	v_add_f32_e32 v190, v118, v190
	v_add_f32_e32 v194, v119, v190
	v_cvt_pk_bf16_f32 v12, v114, v115
	v_cvt_pk_bf16_f32 v13, v116, v117
	v_cvt_pk_bf16_f32 v14, v118, v119
	v_cvt_pk_bf16_f32 v15, v120, v121
	s_waitcnt lgkmcnt(10)
	v_mfma_f32_32x32x16_bf16 v[34:49], v[186:189], v[4:7], v[34:49]
	ds_read_b64_tr_b16 v[190:191], v246 offset:47104
	ds_read_b64_tr_b16 v[192:193], v246 offset:47616
	ds_read_b128 v[224:227], v240 offset:4608
	v_add_f32_e32 v194, v120, v194
	v_add_f32_e32 v194, v121, v194
	v_add_f32_e32 v194, v122, v194
	v_add_f32_e32 v198, v123, v194
	v_cvt_pk_bf16_f32 v4, v122, v123
	v_cvt_pk_bf16_f32 v5, v124, v125
	v_cvt_pk_bf16_f32 v6, v126, v127
	v_cvt_pk_bf16_f32 v7, v128, v129
	s_waitcnt lgkmcnt(10)
	v_mfma_f32_32x32x16_bf16 v[50:65], v[186:189], v[178:181], v[50:65]
	ds_read_b64_tr_b16 v[194:195], v246 offset:51200
	ds_read_b64_tr_b16 v[196:197], v246 offset:51712
	ds_read_b128 v[228:231], v240 offset:6144
	v_add_f32_e32 v198, v124, v198
	v_add_f32_e32 v198, v125, v198
	v_add_f32_e32 v198, v126, v198
	v_add_f32_e32 v198, v127, v198
	s_waitcnt lgkmcnt(10)
; __device__ __forceinline__ int crow(int r,int hi){return (r&3)+8*(r>>2)+4*hi;}
; __device__ __forceinline__ float max3f(float a,float b,float c){float r;asm("v_max3_f32 %0, %1, %2, %3":"=v"(r):"v"(a),"v"(b),"v"(c));return r;}
; __device__ __forceinline__ float max2f(float a,float b){float r;asm("v_max_f32_e32 %0, %1, %2":"=v"(r):"v"(a),"v"(b));return r;}
;   #define PINAB() asm volatile("":"+v"(ma),"+v"(mb))
; template<int THRL,bool FIRST> __device__ __forceinline__ void decide(float rm,St&S,float*wsf,int r32,int hi){
;     ...
;   else if(__any(rm-S.mhat>(float)THRL)){
;     const float dl=__builtin_fmaxf(rm-S.mhat,0.f); S.mhat+=dl;
;     const float f=__builtin_amdgcn_exp2f(-dl); S.l_reg*=f; if(hi==0)wsf[r32]=f;
;     asm volatile("s_waitcnt lgkmcnt(0)":::"memory");
;     #pragma unroll
;     for(int r=0;r<16;++r){ const float fr=wsf[crow(r,hi)];
;       #pragma unroll
;       for(int d=0;d<4;++d)S.o[d][r]*=fr; }
; template<int THRL,bool FIRST> __device__ __forceinline__ void step_main(f32x16&p0,f32x16&p1,f32x16&n0,f32x16&n1,St&S,lds_cptr kpn,lds_cptr qp,lds_cptr vp,float*wsf,int r32,int hi,float&rm){
;     ...
;   PVG(7,pw1,vfd,11, p1[14],p1[15],0.f,0.f, do{}while(0));
;   float ma,mb;
;     ...
;   PVG(8,pw2,vfa,12,0.f,0.f,0.f,0.f, do{ma=max3f(n0[0],n0[1],n1[0]);mb=max3f(n0[2],n0[3],n1[1]);PINAB();}while(0));
;   PVG(9,pw2,vfb,13,0.f,0.f,0.f,0.f, do{ma=max3f(ma,n1[2],n1[3]);mb=max3f(mb,n0[4],n0[5]);PINAB();}while(0));
;   PVG(10,pw2,vfc,14,0.f,0.f,0.f,0.f, do{ma=max3f(ma,n0[6],n0[7]);mb=max3f(mb,n1[4],n1[5]);PINAB();}while(0));
;   PVG(11,pw2,vfd,15,0.f,0.f,0.f,0.f, do{ma=max3f(ma,n1[6],n1[7]);mb=max3f(mb,n0[8],n0[9]);PINAB();}while(0));
;   PVG(12,pw3,vfa,16,0.f,0.f,0.f,0.f, do{ma=max3f(ma,n0[10],n0[11]);mb=max3f(mb,n1[8],n1[9]);PINAB();}while(0));
;   PVG(13,pw3,vfb,16,0.f,0.f,0.f,0.f, do{ma=max3f(ma,n1[10],n1[11]);mb=max3f(mb,n0[12],n0[13]);PINAB();}while(0));
;   PVG(14,pw3,vfc,16,0.f,0.f,0.f,0.f, do{ma=max3f(ma,n0[14],n0[15]);mb=max3f(mb,n1[12],n1[13]);PINAB();}while(0));
;   PVG(15,pw3,vfd,16,0.f,0.f,0.f,0.f, do{ma=max3f(ma,n1[14],n1[15]);ma=max2f(ma,mb);PINAB();}while(0));
;     ...
;   { auto rr=__builtin_amdgcn_permlane32_swap(__float_as_uint(ma),__float_as_uint(ma),false,false); rm=max2f(__uint_as_float(rr[0]),__uint_as_float(rr[1])); }
	v_mfma_f32_32x32x16_bf16 v[66:81], v[186:189], v[182:185], v[66:81]
	ds_read_b64_tr_b16 v[178:179], v246 offset:55296
	ds_read_b64_tr_b16 v[180:181], v246 offset:55808
	ds_read_b128 v[232:235], v240 offset:6656
	v_add_f32_e32 v198, v128, v198
	v_add_f32_e32 v198, v129, v198
	s_waitcnt lgkmcnt(10)
	v_mfma_f32_32x32x16_bf16 v[18:33], v[12:15], v[8:11], v[18:33]
	ds_read_b64_tr_b16 v[182:183], v246 offset:44032
	ds_read_b64_tr_b16 v[184:185], v246 offset:44544
	v_max3_f32 v186, v98, v99, v82
	v_max3_f32 v187, v100, v101, v83
	s_nop 0
	s_waitcnt lgkmcnt(9)
	v_mfma_f32_32x32x16_bf16 v[34:49], v[12:15], v[190:193], v[34:49]
	ds_read_b64_tr_b16 v[8:9], v246 offset:48128
	ds_read_b64_tr_b16 v[10:11], v246 offset:48640
	v_max3_f32 v199, v186, v84, v85
	v_max3_f32 v200, v187, v102, v103
	s_nop 0
	s_waitcnt lgkmcnt(8)
	v_mfma_f32_32x32x16_bf16 v[50:65], v[12:15], v[194:197], v[50:65]
	ds_read_b64_tr_b16 v[186:187], v246 offset:52224
	ds_read_b64_tr_b16 v[188:189], v246 offset:52736
	v_max3_f32 v199, v199, v104, v105
	v_max3_f32 v200, v200, v86, v87
	s_nop 0
	s_waitcnt lgkmcnt(7)
	v_mfma_f32_32x32x16_bf16 v[66:81], v[12:15], v[178:181], v[66:81]
	ds_read_b64_tr_b16 v[190:191], v246 offset:56320
	ds_read_b64_tr_b16 v[192:193], v246 offset:56832
	v_max3_f32 v194, v199, v88, v89
	v_max3_f32 v195, v200, v106, v107
	s_nop 0
	s_waitcnt lgkmcnt(6)
	v_mfma_f32_32x32x16_bf16 v[18:33], v[4:7], v[182:185], v[18:33]
	v_max3_f32 v12, v194, v108, v109
	v_max3_f32 v13, v195, v90, v91
	s_nop 0
	s_waitcnt lgkmcnt(4)
	v_mfma_f32_32x32x16_bf16 v[34:49], v[4:7], v[8:11], v[34:49]
	v_max3_f32 v12, v12, v92, v93
	v_max3_f32 v13, v13, v110, v111
	s_nop 0
	s_waitcnt lgkmcnt(2)
	v_mfma_f32_32x32x16_bf16 v[50:65], v[4:7], v[186:189], v[50:65]
	v_max3_f32 v8, v12, v112, v113
	v_max3_f32 v9, v13, v94, v95
	s_nop 0
	s_waitcnt lgkmcnt(0)
	v_mfma_f32_32x32x16_bf16 v[66:81], v[4:7], v[190:193], v[66:81]
	v_max3_f32 v8, v8, v96, v97
	s_nop 0
	v_max_f32_e32 v8, v8, v9
	s_nop 0
	s_add_u32 s58, s58, 0x180000
	s_addc_u32 s59, s59, 0
	s_add_u32 s50, s50, 0x180000
	s_waitcnt vmcnt(0) lgkmcnt(0)
	s_barrier
	s_addc_u32 s51, s51, 0
	v_mov_b32_e32 v4, v8
	v_add_f32_e32 v251, v17, v198
	s_cmp_lt_u32 s90, s89
	v_permlane32_swap_b32_e32 v8, v4
	v_max_f32_e32 v178, v8, v4
	s_cbranch_scc0 .LBB0_285
.LBB0_278:
	v_cmp_lt_f32_e32 vcc, s69, v178
	s_cbranch_vccz .LBB0_282
	v_max_f32_e32 v126, v178, v178
	v_max_f32_e32 v126, 0, v126
	v_exp_f32_e64 v127, -v126
	s_and_saveexec_b64 s[60:61], s[6:7]
	ds_write_b32 v16, v127
	s_or_b64 exec, exec, s[60:61]
	s_waitcnt lgkmcnt(0)
	v_add_u32_e32 v140, s78, v2
	ds_read_b128 v[128:131], v140 offset:64
	ds_read_b128 v[132:135], v140 offset:96
	ds_read_b128 v[136:139], v140
	ds_read_b128 v[140:143], v140 offset:32
	v_add_f32_e32 v247, v247, v126
	v_sub_f32_e32 v146, v146, v126
	v_sub_f32_e32 v147, v147, v126
	v_sub_f32_e32 v148, v148, v126
	v_sub_f32_e32 v149, v149, v126
	v_sub_f32_e32 v150, v150, v126
	v_sub_f32_e32 v151, v151, v126
	v_sub_f32_e32 v152, v152, v126
	v_sub_f32_e32 v153, v153, v126
	v_sub_f32_e32 v154, v154, v126
	v_sub_f32_e32 v155, v155, v126
	v_sub_f32_e32 v156, v156, v126
	v_sub_f32_e32 v157, v157, v126
	v_sub_f32_e32 v158, v158, v126
	v_sub_f32_e32 v159, v159, v126
	v_sub_f32_e32 v160, v160, v126
	v_sub_f32_e32 v161, v161, v126
	v_sub_f32_e32 v82, v82, v126
	v_sub_f32_e32 v83, v83, v126
	v_sub_f32_e32 v84, v84, v126
	v_sub_f32_e32 v85, v85, v126
	v_sub_f32_e32 v86, v86, v126
	v_sub_f32_e32 v87, v87, v126
	v_sub_f32_e32 v88, v88, v126
	v_sub_f32_e32 v89, v89, v126
	v_sub_f32_e32 v90, v90, v126
	v_sub_f32_e32 v91, v91, v126
	v_sub_f32_e32 v92, v92, v126
	v_sub_f32_e32 v93, v93, v126
	v_sub_f32_e32 v94, v94, v126
	v_sub_f32_e32 v95, v95, v126
	v_sub_f32_e32 v96, v96, v126
	v_sub_f32_e32 v97, v97, v126
	v_sub_f32_e32 v98, v98, v126
	v_sub_f32_e32 v99, v99, v126
	v_sub_f32_e32 v100, v100, v126
	v_sub_f32_e32 v101, v101, v126
	v_sub_f32_e32 v102, v102, v126
	v_sub_f32_e32 v103, v103, v126
	v_sub_f32_e32 v104, v104, v126
	v_sub_f32_e32 v105, v105, v126
	v_sub_f32_e32 v106, v106, v126
	v_sub_f32_e32 v107, v107, v126
	v_sub_f32_e32 v108, v108, v126
	v_sub_f32_e32 v109, v109, v126
	v_sub_f32_e32 v110, v110, v126
	v_sub_f32_e32 v111, v111, v126
	v_sub_f32_e32 v112, v112, v126
	v_sub_f32_e32 v113, v113, v126
	v_mul_f32_e32 v251, v251, v127
	s_waitcnt lgkmcnt(2)
	v_pk_mul_f32 v[30:31], v[30:31], v[132:133]
	v_pk_mul_f32 v[26:27], v[26:27], v[128:129]
	s_waitcnt lgkmcnt(0)
	v_pk_mul_f32 v[22:23], v[22:23], v[140:141]
	v_pk_mul_f32 v[32:33], v[32:33], v[134:135]
	v_pk_mul_f32 v[28:29], v[28:29], v[130:131]
	v_pk_mul_f32 v[24:25], v[24:25], v[142:143]
	v_pk_mul_f32 v[20:21], v[20:21], v[138:139]
	v_pk_mul_f32 v[18:19], v[18:19], v[136:137]
	v_pk_mul_f32 v[46:47], v[46:47], v[132:133]
	v_pk_mul_f32 v[42:43], v[42:43], v[128:129]
	v_pk_mul_f32 v[38:39], v[38:39], v[140:141]
	v_pk_mul_f32 v[48:49], v[48:49], v[134:135]
	v_pk_mul_f32 v[44:45], v[44:45], v[130:131]
	v_pk_mul_f32 v[40:41], v[40:41], v[142:143]
	v_pk_mul_f32 v[36:37], v[36:37], v[138:139]
	v_pk_mul_f32 v[34:35], v[34:35], v[136:137]
	v_pk_mul_f32 v[62:63], v[62:63], v[132:133]
	v_pk_mul_f32 v[58:59], v[58:59], v[128:129]
	v_pk_mul_f32 v[54:55], v[54:55], v[140:141]
	v_pk_mul_f32 v[64:65], v[64:65], v[134:135]
	v_pk_mul_f32 v[60:61], v[60:61], v[130:131]
	v_pk_mul_f32 v[56:57], v[56:57], v[142:143]
	v_pk_mul_f32 v[52:53], v[52:53], v[138:139]
	v_pk_mul_f32 v[50:51], v[50:51], v[136:137]
	v_pk_mul_f32 v[78:79], v[78:79], v[132:133]
	v_pk_mul_f32 v[74:75], v[74:75], v[128:129]
	v_pk_mul_f32 v[70:71], v[70:71], v[140:141]
	v_pk_mul_f32 v[80:81], v[80:81], v[134:135]
	v_pk_mul_f32 v[76:77], v[76:77], v[130:131]
	v_pk_mul_f32 v[72:73], v[72:73], v[142:143]
	v_pk_mul_f32 v[68:69], v[68:69], v[138:139]
	v_pk_mul_f32 v[66:67], v[66:67], v[136:137]
; #define SB() __builtin_amdgcn_sched_barrier(0)
; #define MF32(a,b,c) __builtin_amdgcn_mfma_f32_32x32x16_bf16(a,b,c,0,0,0)
; #define EXP1(x) x=__builtin_amdgcn_exp2f((x)-mh_)
; __device__ __forceinline__ bf16x8 vfrag(lds_cptr vp,int i){ const s16x4 lo=vtr(vp+(i&3)*4096+(i>>2)*1024), hh=vtr(vp+(i&3)*4096+(i>>2)*1024+512); return (bf16x8){lo[0],lo[1],lo[2],lo[3],hh[0],hh[1],hh[2],hh[3]}; }
; __device__ __forceinline__ u32x4 packw(const f32x16&p,int base){ u32x4 w; w[0]=cvtpk_s(p[base],p[base+1]); w[1]=cvtpk_s(p[base+2],p[base+3]); w[2]=cvtpk_s(p[base+4],p[base+5]); w[3]=cvtpk_s(p[base+6],p[base+7]); return w; }
;   #define KF(i) LDSQ(kpn+((i)>>1)*2048+((i)&1)*512)
;   #define QF(d0) LDSQ(qp+(d0)*1024)
; template<int THRL,bool FIRST> __device__ __forceinline__ void step_main(f32x16&p0,f32x16&p1,f32x16&n0,f32x16&n1,St&S,lds_cptr kpn,lds_cptr qp,lds_cptr vp,float*wsf,int r32,int hi,float&rm){
;     ...
;   bf16x8 ka=KF(0),kb=KF(1),kc=KF(2),kd=KF(3),qa=QF(0),qb=QF(1);
;   decide<THRL,FIRST>(rm,S,wsf,r32,hi);
;   u32x4 pw0,pw1,pw2,pw3; const float mh_=S.mhat; const f32x16 z=f32x16{};
;   SB();
;   n0=MF32(ka,qa,z); ka=KF(4); EXP1(p0[0]);EXP1(p0[1]);EXP1(p0[2]); SB();
;   n1=MF32(kb,qa,z); kb=KF(5); qa=QF(2); EXP1(p0[3]);EXP1(p0[4]);EXP1(p0[5]); SB();
;   n0=MF32(kc,qb,n0);   kc=KF(6); EXP1(p0[6]);EXP1(p0[7]);EXP1(p0[8]); SB();
;   n1=MF32(kd,qb,n1);   kd=KF(7); qb=QF(3); EXP1(p0[9]);EXP1(p0[10]);EXP1(p0[11]); SB();
;   bf16x8 vfa=vfrag(vp,0);
;   n0=MF32(ka,qa,n0);   EXP1(p0[12]);EXP1(p0[13]);EXP1(p0[14]); pw0=packw(p0,0); SB();
;   bf16x8 vfb=vfrag(vp,1);
;   n1=MF32(kb,qa,n1);   EXP1(p0[15]);EXP1(p1[0]);EXP1(p1[1]); SB();
;   bf16x8 vfc=vfrag(vp,2);
;   n0=MF32(kc,qb,n0);   EXP1(p1[2]);EXP1(p1[3]);EXP1(p1[4]); pw1=packw(p0,8); SB();
;   bf16x8 vfd=vfrag(vp,3);
;   n1=MF32(kd,qb,n1);   EXP1(p1[5]);EXP1(p1[6]);EXP1(p1[7]); SB();
;     ...
;   float sa=p0[0]+p0[1];
;     ...
;   PVG(0,pw0,vfa,4, p0[2],p0[3],p0[4],p0[5],   do{EXP1(p1[8]);EXP1(p1[9]);}while(0));
;   PVG(1,pw0,vfb,5, p0[6],p0[7],p0[8],p0[9], do{EXP1(p1[10]);EXP1(p1[11]);}while(0));
;   PVG(2,pw0,vfc,6, p0[10],p0[11],p0[12],p0[13], do{EXP1(p1[12]);EXP1(p1[13]);}while(0));
;   PVG(3,pw0,vfd,7, p0[14],p0[15],p1[0],p1[1],   do{EXP1(p1[14]);EXP1(p1[15]);}while(0));
;   PVG(4,pw1,vfa,8, p1[2],p1[3],p1[4],p1[5],   pw2=packw(p1,0));
;   PVG(5,pw1,vfb,9, p1[6],p1[7],p1[8],p1[9], pw3=packw(p1,8));
.LBB0_282:
	s_add_i32 s4, s88, 0x2000
	s_cmpk_lg_i32 s88, 0x4000
	s_cselect_b32 s91, s4, 0
	v_mfma_f32_32x32x16_bf16 v[130:145], v[204:207], v[164:167], v[146:161]
	s_add_i32 s4, s91, s84
	s_mov_b32 s5, m0
	s_mov_b32 m0, s4
	s_nop 0
	global_load_lds_dwordx4 v252, s[58:59]
	s_mov_b32 m0, s5
	v_exp_f32_e32 v190, v98
	v_exp_f32_e32 v191, v99
	v_exp_f32_e32 v192, v100
	v_mfma_f32_32x32x16_bf16 v[114:129], v[208:211], v[164:167], v[146:161]
	s_mov_b32 s4, m0
	s_mov_b32 m0, s79
	s_nop 0
	global_load_lds_dwordx4 v250, s[50:51]
	s_mov_b32 m0, s4
	v_exp_f32_e32 v193, v101
	v_exp_f32_e32 v194, v102
	v_exp_f32_e32 v195, v103
	v_mfma_f32_32x32x16_bf16 v[130:145], v[212:215], v[168:171], v[130:145]
	s_add_u32 s60, s50, 0x80
	s_addc_u32 s61, s51, 0
	s_mov_b32 s4, m0
	s_mov_b32 m0, s41
	s_nop 0
	global_load_lds_dwordx4 v250, s[60:61]
	s_mov_b32 m0, s4
	v_exp_f32_e32 v196, v104
	v_exp_f32_e32 v197, v105
	v_exp_f32_e32 v198, v106
	v_mfma_f32_32x32x16_bf16 v[114:129], v[216:219], v[168:171], v[114:129]
	v_exp_f32_e32 v17, v107
	v_exp_f32_e32 v199, v108
	v_exp_f32_e32 v200, v109
	v_mfma_f32_32x32x16_bf16 v[130:145], v[220:223], v[172:175], v[130:145]
	v_exp_f32_e32 v201, v110
	ds_read_b64_tr_b16 v[4:5], v246 offset:24576
	ds_read_b64_tr_b16 v[6:7], v246 offset:25088
	v_exp_f32_e32 v202, v111
	v_exp_f32_e32 v178, v112
	v_cvt_pk_bf16_f32 v8, v190, v191
	v_cvt_pk_bf16_f32 v9, v192, v193
	v_cvt_pk_bf16_f32 v10, v194, v195
	v_cvt_pk_bf16_f32 v11, v196, v197
	v_mfma_f32_32x32x16_bf16 v[114:129], v[224:227], v[172:175], v[114:129]
	ds_read_b64_tr_b16 v[106:107], v246 offset:28672
	ds_read_b64_tr_b16 v[108:109], v246 offset:29184
	v_exp_f32_e32 v180, v82
	v_exp_f32_e32 v179, v113
	v_exp_f32_e32 v181, v83
	v_mfma_f32_32x32x16_bf16 v[130:145], v[228:231], v[236:239], v[130:145]
	ds_read_b64_tr_b16 v[110:111], v246 offset:32768
	ds_read_b64_tr_b16 v[112:113], v246 offset:33280
	v_exp_f32_e32 v182, v84
	v_exp_f32_e32 v183, v85
	v_exp_f32_e32 v184, v86
	v_cvt_pk_bf16_f32 v82, v198, v17
	v_cvt_pk_bf16_f32 v83, v199, v200
	v_cvt_pk_bf16_f32 v84, v201, v202
	v_cvt_pk_bf16_f32 v85, v178, v179
	v_mfma_f32_32x32x16_bf16 v[114:129], v[232:235], v[236:239], v[114:129]
	v_add_u32_e32 v240, s88, v249
	ds_read_b64_tr_b16 v[98:99], v246 offset:36864
	ds_read_b64_tr_b16 v[100:101], v246 offset:37376
	v_exp_f32_e32 v185, v87
	v_exp_f32_e32 v186, v88
	v_exp_f32_e32 v187, v89
	s_waitcnt lgkmcnt(6)
	v_mfma_f32_32x32x16_bf16 v[18:33], v[8:11], v[4:7], v[18:33]
	ds_read_b128 v[204:207], v240
	v_add_f32_e32 v86, v190, v191
	ds_read_b64_tr_b16 v[12:13], v246 offset:25600
	ds_read_b64_tr_b16 v[14:15], v246 offset:26112
	v_add_f32_e32 v86, v192, v86
	v_exp_f32_e32 v103, v91
	v_add_f32_e32 v4, v193, v86
	v_add_f32_e32 v4, v194, v4
	v_add_f32_e32 v86, v195, v4
	v_exp_f32_e32 v102, v90
	s_waitcnt lgkmcnt(7)
	v_mfma_f32_32x32x16_bf16 v[34:49], v[8:11], v[106:109], v[34:49]
	ds_read_b64_tr_b16 v[4:5], v246 offset:29696
	ds_read_b64_tr_b16 v[6:7], v246 offset:30208
	ds_read_b128 v[208:211], v240 offset:512
	v_add_f32_e32 v86, v196, v86
	v_add_f32_e32 v86, v197, v86
	v_add_f32_e32 v86, v198, v86
	v_exp_f32_e32 v104, v92
	v_add_f32_e32 v17, v17, v86
	v_exp_f32_e32 v105, v93
	s_waitcnt lgkmcnt(8)
	v_mfma_f32_32x32x16_bf16 v[50:65], v[8:11], v[110:113], v[50:65]
	ds_read_b64_tr_b16 v[86:87], v246 offset:33792
	ds_read_b64_tr_b16 v[88:89], v246 offset:34304
	ds_read_b128 v[212:215], v240 offset:2048
	v_add_f32_e32 v17, v199, v17
	v_add_f32_e32 v17, v200, v17
	v_add_f32_e32 v17, v201, v17
	v_exp_f32_e32 v106, v94
	v_add_f32_e32 v17, v202, v17
	v_exp_f32_e32 v107, v95
	s_waitcnt lgkmcnt(9)
	v_mfma_f32_32x32x16_bf16 v[66:81], v[8:11], v[98:101], v[66:81]
	ds_read_b64_tr_b16 v[90:91], v246 offset:37888
	ds_read_b64_tr_b16 v[92:93], v246 offset:38400
	ds_read_b128 v[216:219], v240 offset:2560
	v_add_f32_e32 v17, v178, v17
	v_add_f32_e32 v8, v179, v17
	v_add_f32_e32 v8, v180, v8
	v_exp_f32_e32 v108, v96
	v_add_f32_e32 v17, v181, v8
	v_exp_f32_e32 v109, v97
	s_waitcnt lgkmcnt(9)
; __device__ __forceinline__ float max3f(float a,float b,float c){float r;asm("v_max3_f32 %0, %1, %2, %3":"=v"(r):"v"(a),"v"(b),"v"(c));return r;}
; __device__ __forceinline__ float max2f(float a,float b){float r;asm("v_max_f32_e32 %0, %1, %2":"=v"(r):"v"(a),"v"(b));return r;}
;   #define PVG(i,PW,VF,NEXTI,X0,X1,Y0,Y1,EXTRA) do{ S.o[(i)&3]=MF32(__builtin_bit_cast(bf16x8,PW),VF,S.o[(i)&3]); if((NEXTI)<16){ VF=vfrag(vp,(NEXTI)<16?(NEXTI):0); } sa+=X0; sa+=X1; sa+=Y0; sa+=Y1; EXTRA; SB(); }while(0)
;   #define PINAB() asm volatile("":"+v"(ma),"+v"(mb))
; template<int THRL,bool FIRST> __device__ __forceinline__ void step_main(f32x16&p0,f32x16&p1,f32x16&n0,f32x16&n1,St&S,lds_cptr kpn,lds_cptr qp,lds_cptr vp,float*wsf,int r32,int hi,float&rm){
;     ...
;   PVG(7,pw1,vfd,11, p1[14],p1[15],0.f,0.f, do{}while(0));
;   float ma,mb;
;     ...
;   PVG(8,pw2,vfa,12,0.f,0.f,0.f,0.f, do{ma=max3f(n0[0],n0[1],n1[0]);mb=max3f(n0[2],n0[3],n1[1]);PINAB();}while(0));
;   PVG(9,pw2,vfb,13,0.f,0.f,0.f,0.f, do{ma=max3f(ma,n1[2],n1[3]);mb=max3f(mb,n0[4],n0[5]);PINAB();}while(0));
;   PVG(10,pw2,vfc,14,0.f,0.f,0.f,0.f, do{ma=max3f(ma,n0[6],n0[7]);mb=max3f(mb,n1[4],n1[5]);PINAB();}while(0));
;   PVG(11,pw2,vfd,15,0.f,0.f,0.f,0.f, do{ma=max3f(ma,n1[6],n1[7]);mb=max3f(mb,n0[8],n0[9]);PINAB();}while(0));
;   PVG(12,pw3,vfa,16,0.f,0.f,0.f,0.f, do{ma=max3f(ma,n0[10],n0[11]);mb=max3f(mb,n1[8],n1[9]);PINAB();}while(0));
;   PVG(13,pw3,vfb,16,0.f,0.f,0.f,0.f, do{ma=max3f(ma,n1[10],n1[11]);mb=max3f(mb,n0[12],n0[13]);PINAB();}while(0));
;   PVG(14,pw3,vfc,16,0.f,0.f,0.f,0.f, do{ma=max3f(ma,n0[14],n0[15]);mb=max3f(mb,n1[12],n1[13]);PINAB();}while(0));
;   PVG(15,pw3,vfd,16,0.f,0.f,0.f,0.f, do{ma=max3f(ma,n1[14],n1[15]);ma=max2f(ma,mb);PINAB();}while(0));
;     ...
;   { auto rr=__builtin_amdgcn_permlane32_swap(__float_as_uint(ma),__float_as_uint(ma),false,false); rm=max2f(__uint_as_float(rr[0]),__uint_as_float(rr[1])); }
	v_mfma_f32_32x32x16_bf16 v[18:33], v[82:85], v[12:15], v[18:33]
	ds_read_b64_tr_b16 v[8:9], v246 offset:26624
	ds_read_b64_tr_b16 v[10:11], v246 offset:27136
	ds_read_b128 v[220:223], v240 offset:4096
	v_add_f32_e32 v17, v182, v17
	v_add_f32_e32 v17, v183, v17
	v_add_f32_e32 v17, v184, v17
	v_add_f32_e32 v17, v185, v17
	v_cvt_pk_bf16_f32 v12, v180, v181
	v_cvt_pk_bf16_f32 v13, v182, v183
	v_cvt_pk_bf16_f32 v14, v184, v185
	v_cvt_pk_bf16_f32 v15, v186, v187
	s_waitcnt lgkmcnt(10)
	v_mfma_f32_32x32x16_bf16 v[34:49], v[82:85], v[4:7], v[34:49]
	ds_read_b64_tr_b16 v[94:95], v246 offset:30720
	ds_read_b64_tr_b16 v[96:97], v246 offset:31232
	ds_read_b128 v[224:227], v240 offset:4608
	v_add_f32_e32 v17, v186, v17
	v_add_f32_e32 v17, v187, v17
	v_add_f32_e32 v17, v102, v17
	v_add_f32_e32 v17, v103, v17
	v_cvt_pk_bf16_f32 v4, v102, v103
	v_cvt_pk_bf16_f32 v5, v104, v105
	v_cvt_pk_bf16_f32 v6, v106, v107
	v_cvt_pk_bf16_f32 v7, v108, v109
	s_waitcnt lgkmcnt(10)
	v_mfma_f32_32x32x16_bf16 v[50:65], v[82:85], v[86:89], v[50:65]
	ds_read_b64_tr_b16 v[98:99], v246 offset:34816
	ds_read_b64_tr_b16 v[100:101], v246 offset:35328
	ds_read_b128 v[228:231], v240 offset:6144
	v_add_f32_e32 v17, v104, v17
	v_add_f32_e32 v17, v105, v17
	v_add_f32_e32 v17, v106, v17
	v_add_f32_e32 v17, v107, v17
	s_waitcnt lgkmcnt(10)
	v_mfma_f32_32x32x16_bf16 v[66:81], v[82:85], v[90:93], v[66:81]
	ds_read_b64_tr_b16 v[86:87], v246 offset:38912
	ds_read_b64_tr_b16 v[88:89], v246 offset:39424
	ds_read_b128 v[232:235], v240 offset:6656
	v_add_f32_e32 v17, v108, v17
	v_add_f32_e32 v17, v109, v17
	s_waitcnt lgkmcnt(10)
	v_mfma_f32_32x32x16_bf16 v[18:33], v[12:15], v[8:11], v[18:33]
	ds_read_b64_tr_b16 v[82:83], v246 offset:27648
	ds_read_b64_tr_b16 v[84:85], v246 offset:28160
	v_max3_f32 v90, v130, v131, v114
	v_max3_f32 v91, v132, v133, v115
	s_nop 0
	s_waitcnt lgkmcnt(9)
	v_mfma_f32_32x32x16_bf16 v[34:49], v[12:15], v[94:97], v[34:49]
	ds_read_b64_tr_b16 v[8:9], v246 offset:31744
	ds_read_b64_tr_b16 v[10:11], v246 offset:32256
	v_max3_f32 v102, v90, v116, v117
	v_max3_f32 v103, v91, v134, v135
	s_nop 0
	s_waitcnt lgkmcnt(8)
	v_mfma_f32_32x32x16_bf16 v[50:65], v[12:15], v[98:101], v[50:65]
	ds_read_b64_tr_b16 v[90:91], v246 offset:35840
	ds_read_b64_tr_b16 v[92:93], v246 offset:36352
	v_max3_f32 v102, v102, v136, v137
	v_max3_f32 v103, v103, v118, v119
	s_nop 0
	s_waitcnt lgkmcnt(7)
	v_mfma_f32_32x32x16_bf16 v[66:81], v[12:15], v[86:89], v[66:81]
	ds_read_b64_tr_b16 v[94:95], v246 offset:39936
	ds_read_b64_tr_b16 v[96:97], v246 offset:40448
	v_max3_f32 v98, v102, v120, v121
	v_max3_f32 v99, v103, v138, v139
	s_nop 0
	s_waitcnt lgkmcnt(6)
	v_mfma_f32_32x32x16_bf16 v[18:33], v[4:7], v[82:85], v[18:33]
	v_max3_f32 v12, v98, v140, v141
	v_max3_f32 v13, v99, v122, v123
	s_nop 0
	s_waitcnt lgkmcnt(4)
	v_mfma_f32_32x32x16_bf16 v[34:49], v[4:7], v[8:11], v[34:49]
	v_max3_f32 v12, v12, v124, v125
	v_max3_f32 v13, v13, v142, v143
	s_nop 0
	s_waitcnt lgkmcnt(2)
	v_mfma_f32_32x32x16_bf16 v[50:65], v[4:7], v[90:93], v[50:65]
	v_max3_f32 v8, v12, v144, v145
	v_max3_f32 v9, v13, v126, v127
	s_nop 0
	s_waitcnt lgkmcnt(0)
	v_mfma_f32_32x32x16_bf16 v[66:81], v[4:7], v[94:97], v[66:81]
	v_max3_f32 v8, v8, v128, v129
	s_nop 0
	v_max_f32_e32 v8, v8, v9
	s_nop 0
	v_mov_b32_e32 v163, v8
	s_waitcnt vmcnt(0) lgkmcnt(0)
	s_barrier
	v_permlane32_swap_b32_e32 v8, v163
	v_max_f32_e32 v94, v8, v163
	v_add_f32_e32 v17, v251, v17
	v_cmp_lt_f32_e32 vcc, s69, v94
	s_cbranch_vccz .LBB0_277
	v_max_f32_e32 v94, v94, v94
	v_max_f32_e32 v94, 0, v94
	v_exp_f32_e64 v95, -v94
	s_and_saveexec_b64 s[60:61], s[6:7]
	s_cbranch_execz .LBB0_276
	ds_write_b32 v16, v95
	s_branch .LBB0_276

; #define SB() __builtin_amdgcn_sched_barrier(0)
; #define MF32(a,b,c) __builtin_amdgcn_mfma_f32_32x32x16_bf16(a,b,c,0,0,0)
; #define EXP1(x) x=__builtin_amdgcn_exp2f((x)-mh_)
; __device__ __forceinline__ bf16x8 vfrag(lds_cptr vp,int i){ const s16x4 lo=vtr(vp+(i&3)*4096+(i>>2)*1024), hh=vtr(vp+(i&3)*4096+(i>>2)*1024+512); return (bf16x8){lo[0],lo[1],lo[2],lo[3],hh[0],hh[1],hh[2],hh[3]}; }
; __device__ __forceinline__ u32x4 packw(const f32x16&p,int base){ u32x4 w; w[0]=cvtpk_s(p[base],p[base+1]); w[1]=cvtpk_s(p[base+2],p[base+3]); w[2]=cvtpk_s(p[base+4],p[base+5]); w[3]=cvtpk_s(p[base+6],p[base+7]); return w; }
;   #define KF(i) LDSQ(kpn+((i)>>1)*2048+((i)&1)*512)
;   #define QF(d0) LDSQ(qp+(d0)*1024)
; template<int THRL,bool FIRST> __device__ __forceinline__ void step_main(f32x16&p0,f32x16&p1,f32x16&n0,f32x16&n1,St&S,lds_cptr kpn,lds_cptr qp,lds_cptr vp,float*wsf,int r32,int hi,float&rm){
;     ...
;   bf16x8 ka=KF(0),kb=KF(1),kc=KF(2),kd=KF(3),qa=QF(0),qb=QF(1);
;   decide<THRL,FIRST>(rm,S,wsf,r32,hi);
;   u32x4 pw0,pw1,pw2,pw3; const float mh_=S.mhat; const f32x16 z=f32x16{};
;   SB();
;   n0=MF32(ka,qa,z); ka=KF(4); EXP1(p0[0]);EXP1(p0[1]);EXP1(p0[2]); SB();
;   n1=MF32(kb,qa,z); kb=KF(5); qa=QF(2); EXP1(p0[3]);EXP1(p0[4]);EXP1(p0[5]); SB();
;   n0=MF32(kc,qb,n0);   kc=KF(6); EXP1(p0[6]);EXP1(p0[7]);EXP1(p0[8]); SB();
;   n1=MF32(kd,qb,n1);   kd=KF(7); qb=QF(3); EXP1(p0[9]);EXP1(p0[10]);EXP1(p0[11]); SB();
;   bf16x8 vfa=vfrag(vp,0);
;   n0=MF32(ka,qa,n0);   EXP1(p0[12]);EXP1(p0[13]);EXP1(p0[14]); pw0=packw(p0,0); SB();
;   bf16x8 vfb=vfrag(vp,1);
;   n1=MF32(kb,qa,n1);   EXP1(p0[15]);EXP1(p1[0]);EXP1(p1[1]); SB();
;   bf16x8 vfc=vfrag(vp,2);
;   n0=MF32(kc,qb,n0);   EXP1(p1[2]);EXP1(p1[3]);EXP1(p1[4]); pw1=packw(p0,8); SB();
;   bf16x8 vfd=vfrag(vp,3);
;   n1=MF32(kd,qb,n1);   EXP1(p1[5]);EXP1(p1[6]);EXP1(p1[7]); SB();
;     ...
;   float sa=p0[0]+p0[1];
;     ...
;   PVG(0,pw0,vfa,4, p0[2],p0[3],p0[4],p0[5],   do{EXP1(p1[8]);EXP1(p1[9]);}while(0));
;   PVG(1,pw0,vfb,5, p0[6],p0[7],p0[8],p0[9], do{EXP1(p1[10]);EXP1(p1[11]);}while(0));
;   PVG(2,pw0,vfc,6, p0[10],p0[11],p0[12],p0[13], do{EXP1(p1[12]);EXP1(p1[13]);}while(0));
;   PVG(3,pw0,vfd,7, p0[14],p0[15],p1[0],p1[1],   do{EXP1(p1[14]);EXP1(p1[15]);}while(0));
;   PVG(4,pw1,vfa,8, p1[2],p1[3],p1[4],p1[5],   pw2=packw(p1,0));
;   PVG(5,pw1,vfb,9, p1[6],p1[7],p1[8],p1[9], pw3=packw(p1,8));
.LBB0_435:
	s_add_i32 s4, s89, 0x2000
	s_cmpk_lg_i32 s89, 0x4000
	s_cselect_b32 s86, s4, 0
	s_add_i32 s88, s88, 2
	v_mfma_f32_32x32x16_bf16 v[98:113], v[204:207], v[164:167], v[146:161]
	s_add_i32 s4, s86, s80
	s_add_u32 s58, s50, 0xc0000
	s_addc_u32 s59, s51, 0
	s_mov_b32 s5, m0
	s_mov_b32 m0, s4
	s_nop 0
	global_load_lds_dwordx4 v252, s[58:59]
	s_mov_b32 m0, s5
	v_exp_f32_e32 v130, v130
	v_exp_f32_e32 v131, v131
	v_exp_f32_e32 v132, v132
	v_exp_f32_e32 v133, v133
	v_exp_f32_e32 v134, v134
	v_exp_f32_e32 v135, v135
	v_mfma_f32_32x32x16_bf16 v[82:97], v[208:211], v[164:167], v[146:161]
	s_add_u32 s58, s48, 0xc0000
	s_addc_u32 s59, s49, 0
	s_mov_b32 s4, m0
	s_mov_b32 m0, s78
	s_nop 0
	global_load_lds_dwordx4 v250, s[58:59]
	s_mov_b32 m0, s4
	v_mfma_f32_32x32x16_bf16 v[98:113], v[212:215], v[168:171], v[98:113]
	s_add_u32 s58, s48, 0xc0080
	s_addc_u32 s59, s49, 0
	s_mov_b32 s4, m0
	s_mov_b32 m0, s79
	s_nop 0
	global_load_lds_dwordx4 v250, s[58:59]
	s_mov_b32 m0, s4
	v_exp_f32_e32 v136, v136
	v_exp_f32_e32 v137, v137
	v_exp_f32_e32 v138, v138
	v_mfma_f32_32x32x16_bf16 v[82:97], v[216:219], v[168:171], v[82:97]
	v_exp_f32_e32 v139, v139
	v_exp_f32_e32 v140, v140
	v_exp_f32_e32 v141, v141
	v_mfma_f32_32x32x16_bf16 v[98:113], v[220:223], v[172:175], v[98:113]
	v_exp_f32_e32 v142, v142
	ds_read_b64_tr_b16 v[4:5], v246 offset:40960
	ds_read_b64_tr_b16 v[6:7], v246 offset:41472
	v_exp_f32_e32 v143, v143
	v_exp_f32_e32 v144, v144
	v_cvt_pk_bf16_f32 v8, v130, v131
	v_cvt_pk_bf16_f32 v9, v132, v133
	v_cvt_pk_bf16_f32 v10, v134, v135
	v_cvt_pk_bf16_f32 v11, v136, v137
	v_mfma_f32_32x32x16_bf16 v[82:97], v[224:227], v[172:175], v[82:97]
	ds_read_b64_tr_b16 v[178:179], v246 offset:45056
	ds_read_b64_tr_b16 v[180:181], v246 offset:45568
	v_exp_f32_e32 v145, v145
	v_exp_f32_e32 v114, v114
	v_exp_f32_e32 v115, v115
	v_mfma_f32_32x32x16_bf16 v[98:113], v[228:231], v[236:239], v[98:113]
	ds_read_b64_tr_b16 v[182:183], v246 offset:49152
	ds_read_b64_tr_b16 v[184:185], v246 offset:49664
	v_exp_f32_e32 v116, v116
	v_exp_f32_e32 v117, v117
	v_exp_f32_e32 v118, v118
	v_cvt_pk_bf16_f32 v186, v138, v139
	v_cvt_pk_bf16_f32 v187, v140, v141
	v_cvt_pk_bf16_f32 v188, v142, v143
	v_cvt_pk_bf16_f32 v189, v144, v145
	v_mfma_f32_32x32x16_bf16 v[82:97], v[232:235], v[236:239], v[82:97]
	v_add_u32_e32 v240, s89, v249
	ds_read_b64_tr_b16 v[190:191], v246 offset:53248
	ds_read_b64_tr_b16 v[192:193], v246 offset:53760
	v_exp_f32_e32 v119, v119
	v_exp_f32_e32 v120, v120
	v_exp_f32_e32 v121, v121
	s_waitcnt lgkmcnt(6)
	v_mfma_f32_32x32x16_bf16 v[18:33], v[8:11], v[4:7], v[18:33]
	ds_read_b64_tr_b16 v[12:13], v246 offset:41984
	ds_read_b64_tr_b16 v[14:15], v246 offset:42496
	ds_read_b128 v[204:207], v240
	v_add_f32_e32 v194, v130, v131
	v_exp_f32_e32 v122, v122
	v_exp_f32_e32 v123, v123
	v_add_f32_e32 v194, v132, v194
	v_add_f32_e32 v4, v133, v194
	v_add_f32_e32 v4, v134, v4
	v_add_f32_e32 v194, v135, v4
	s_waitcnt lgkmcnt(7)
	v_mfma_f32_32x32x16_bf16 v[34:49], v[8:11], v[178:181], v[34:49]
	ds_read_b64_tr_b16 v[4:5], v246 offset:46080
	ds_read_b64_tr_b16 v[6:7], v246 offset:46592
	ds_read_b128 v[208:211], v240 offset:512
	v_exp_f32_e32 v124, v124
	v_exp_f32_e32 v125, v125
	v_add_f32_e32 v194, v136, v194
	v_add_f32_e32 v178, v137, v194
	v_add_f32_e32 v178, v138, v178
	v_add_f32_e32 v194, v139, v178
	s_waitcnt lgkmcnt(8)
	v_mfma_f32_32x32x16_bf16 v[50:65], v[8:11], v[182:185], v[50:65]
	ds_read_b64_tr_b16 v[178:179], v246 offset:50176
	ds_read_b64_tr_b16 v[180:181], v246 offset:50688
	ds_read_b128 v[212:215], v240 offset:2048
	v_exp_f32_e32 v126, v126
	v_exp_f32_e32 v127, v127
	v_add_f32_e32 v194, v140, v194
	v_add_f32_e32 v182, v141, v194
	v_add_f32_e32 v182, v142, v182
	v_add_f32_e32 v194, v143, v182
	s_waitcnt lgkmcnt(9)
	v_mfma_f32_32x32x16_bf16 v[66:81], v[8:11], v[190:193], v[66:81]
	ds_read_b64_tr_b16 v[182:183], v246 offset:54272
	ds_read_b64_tr_b16 v[184:185], v246 offset:54784
	ds_read_b128 v[216:219], v240 offset:2560
	v_exp_f32_e32 v128, v128
	v_exp_f32_e32 v129, v129
	v_add_f32_e32 v194, v144, v194
	v_add_f32_e32 v8, v145, v194
	v_add_f32_e32 v8, v114, v8
	v_add_f32_e32 v190, v115, v8
	s_waitcnt lgkmcnt(10)
	v_mfma_f32_32x32x16_bf16 v[18:33], v[186:189], v[12:15], v[18:33]
	ds_read_b64_tr_b16 v[8:9], v246 offset:43008
	ds_read_b64_tr_b16 v[10:11], v246 offset:43520
	ds_read_b128 v[220:223], v240 offset:4096
	v_add_f32_e32 v190, v116, v190
	v_add_f32_e32 v190, v117, v190
	v_add_f32_e32 v190, v118, v190
	v_add_f32_e32 v194, v119, v190
	v_cvt_pk_bf16_f32 v12, v114, v115
	v_cvt_pk_bf16_f32 v13, v116, v117
	v_cvt_pk_bf16_f32 v14, v118, v119
	v_cvt_pk_bf16_f32 v15, v120, v121
	s_waitcnt lgkmcnt(10)
	v_mfma_f32_32x32x16_bf16 v[34:49], v[186:189], v[4:7], v[34:49]
	ds_read_b64_tr_b16 v[190:191], v246 offset:47104
	ds_read_b64_tr_b16 v[192:193], v246 offset:47616
	ds_read_b128 v[224:227], v240 offset:4608
	v_add_f32_e32 v194, v120, v194
	v_add_f32_e32 v194, v121, v194
	v_add_f32_e32 v194, v122, v194
	v_add_f32_e32 v198, v123, v194
	v_cvt_pk_bf16_f32 v4, v122, v123
	v_cvt_pk_bf16_f32 v5, v124, v125
	v_cvt_pk_bf16_f32 v6, v126, v127
	v_cvt_pk_bf16_f32 v7, v128, v129
	s_waitcnt lgkmcnt(10)
	v_mfma_f32_32x32x16_bf16 v[50:65], v[186:189], v[178:181], v[50:65]
	ds_read_b64_tr_b16 v[194:195], v246 offset:51200
	ds_read_b64_tr_b16 v[196:197], v246 offset:51712
	ds_read_b128 v[228:231], v240 offset:6144
	v_add_f32_e32 v198, v124, v198
	v_add_f32_e32 v198, v125, v198
	v_add_f32_e32 v198, v126, v198
	v_add_f32_e32 v198, v127, v198
	s_waitcnt lgkmcnt(10)
; __device__ __forceinline__ int crow(int r,int hi){return (r&3)+8*(r>>2)+4*hi;}
; __device__ __forceinline__ float max3f(float a,float b,float c){float r;asm("v_max3_f32 %0, %1, %2, %3":"=v"(r):"v"(a),"v"(b),"v"(c));return r;}
; __device__ __forceinline__ float max2f(float a,float b){float r;asm("v_max_f32_e32 %0, %1, %2":"=v"(r):"v"(a),"v"(b));return r;}
;   #define PINAB() asm volatile("":"+v"(ma),"+v"(mb))
; template<int THRL,bool FIRST> __device__ __forceinline__ void decide(float rm,St&S,float*wsf,int r32,int hi){
;     ...
;   else if(__any(rm-S.mhat>(float)THRL)){
;     const float dl=__builtin_fmaxf(rm-S.mhat,0.f); S.mhat+=dl;
;     const float f=__builtin_amdgcn_exp2f(-dl); S.l_reg*=f; if(hi==0)wsf[r32]=f;
;     asm volatile("s_waitcnt lgkmcnt(0)":::"memory");
;     #pragma unroll
;     for(int r=0;r<16;++r){ const float fr=wsf[crow(r,hi)];
;       #pragma unroll
;       for(int d=0;d<4;++d)S.o[d][r]*=fr; }
; template<int THRL,bool FIRST> __device__ __forceinline__ void step_main(f32x16&p0,f32x16&p1,f32x16&n0,f32x16&n1,St&S,lds_cptr kpn,lds_cptr qp,lds_cptr vp,float*wsf,int r32,int hi,float&rm){
;     ...
;   PVG(7,pw1,vfd,11, p1[14],p1[15],0.f,0.f, do{}while(0));
;   float ma,mb;
;     ...
;   PVG(8,pw2,vfa,12,0.f,0.f,0.f,0.f, do{ma=max3f(n0[0],n0[1],n1[0]);mb=max3f(n0[2],n0[3],n1[1]);PINAB();}while(0));
;   PVG(9,pw2,vfb,13,0.f,0.f,0.f,0.f, do{ma=max3f(ma,n1[2],n1[3]);mb=max3f(mb,n0[4],n0[5]);PINAB();}while(0));
;   PVG(10,pw2,vfc,14,0.f,0.f,0.f,0.f, do{ma=max3f(ma,n0[6],n0[7]);mb=max3f(mb,n1[4],n1[5]);PINAB();}while(0));
;   PVG(11,pw2,vfd,15,0.f,0.f,0.f,0.f, do{ma=max3f(ma,n1[6],n1[7]);mb=max3f(mb,n0[8],n0[9]);PINAB();}while(0));
;   PVG(12,pw3,vfa,16,0.f,0.f,0.f,0.f, do{ma=max3f(ma,n0[10],n0[11]);mb=max3f(mb,n1[8],n1[9]);PINAB();}while(0));
;   PVG(13,pw3,vfb,16,0.f,0.f,0.f,0.f, do{ma=max3f(ma,n1[10],n1[11]);mb=max3f(mb,n0[12],n0[13]);PINAB();}while(0));
;   PVG(14,pw3,vfc,16,0.f,0.f,0.f,0.f, do{ma=max3f(ma,n0[14],n0[15]);mb=max3f(mb,n1[12],n1[13]);PINAB();}while(0));
;   PVG(15,pw3,vfd,16,0.f,0.f,0.f,0.f, do{ma=max3f(ma,n1[14],n1[15]);ma=max2f(ma,mb);PINAB();}while(0));
;     ...
;   { auto rr=__builtin_amdgcn_permlane32_swap(__float_as_uint(ma),__float_as_uint(ma),false,false); rm=max2f(__uint_as_float(rr[0]),__uint_as_float(rr[1])); }
	v_mfma_f32_32x32x16_bf16 v[66:81], v[186:189], v[182:185], v[66:81]
	ds_read_b64_tr_b16 v[178:179], v246 offset:55296
	ds_read_b64_tr_b16 v[180:181], v246 offset:55808
	ds_read_b128 v[232:235], v240 offset:6656
	v_add_f32_e32 v198, v128, v198
	v_add_f32_e32 v198, v129, v198
	s_waitcnt lgkmcnt(10)
	v_mfma_f32_32x32x16_bf16 v[18:33], v[12:15], v[8:11], v[18:33]
	ds_read_b64_tr_b16 v[182:183], v246 offset:44032
	ds_read_b64_tr_b16 v[184:185], v246 offset:44544
	v_max3_f32 v186, v98, v99, v82
	v_max3_f32 v187, v100, v101, v83
	s_nop 0
	s_waitcnt lgkmcnt(9)
	v_mfma_f32_32x32x16_bf16 v[34:49], v[12:15], v[190:193], v[34:49]
	ds_read_b64_tr_b16 v[8:9], v246 offset:48128
	ds_read_b64_tr_b16 v[10:11], v246 offset:48640
	v_max3_f32 v199, v186, v84, v85
	v_max3_f32 v200, v187, v102, v103
	s_nop 0
	s_waitcnt lgkmcnt(8)
	v_mfma_f32_32x32x16_bf16 v[50:65], v[12:15], v[194:197], v[50:65]
	ds_read_b64_tr_b16 v[186:187], v246 offset:52224
	ds_read_b64_tr_b16 v[188:189], v246 offset:52736
	v_max3_f32 v199, v199, v104, v105
	v_max3_f32 v200, v200, v86, v87
	s_nop 0
	s_waitcnt lgkmcnt(7)
	v_mfma_f32_32x32x16_bf16 v[66:81], v[12:15], v[178:181], v[66:81]
	ds_read_b64_tr_b16 v[190:191], v246 offset:56320
	ds_read_b64_tr_b16 v[192:193], v246 offset:56832
	v_max3_f32 v194, v199, v88, v89
	v_max3_f32 v195, v200, v106, v107
	s_nop 0
	s_waitcnt lgkmcnt(6)
	v_mfma_f32_32x32x16_bf16 v[18:33], v[4:7], v[182:185], v[18:33]
	v_max3_f32 v12, v194, v108, v109
	v_max3_f32 v13, v195, v90, v91
	s_nop 0
	s_waitcnt lgkmcnt(4)
	v_mfma_f32_32x32x16_bf16 v[34:49], v[4:7], v[8:11], v[34:49]
	v_max3_f32 v12, v12, v92, v93
	v_max3_f32 v13, v13, v110, v111
	s_nop 0
	s_waitcnt lgkmcnt(2)
	v_mfma_f32_32x32x16_bf16 v[50:65], v[4:7], v[186:189], v[50:65]
	v_max3_f32 v8, v12, v112, v113
	v_max3_f32 v9, v13, v94, v95
	s_nop 0
	s_waitcnt lgkmcnt(0)
	v_mfma_f32_32x32x16_bf16 v[66:81], v[4:7], v[190:193], v[66:81]
	v_max3_f32 v8, v8, v96, v97
	s_nop 0
	v_max_f32_e32 v8, v8, v9
	s_nop 0
	s_add_u32 s50, s50, 0x180000
	s_addc_u32 s51, s51, 0
	s_add_u32 s48, s48, 0x180000
	s_waitcnt vmcnt(0) lgkmcnt(0)
	s_barrier
	s_addc_u32 s49, s49, 0
	v_mov_b32_e32 v4, v8
	v_add_f32_e32 v251, v17, v198
	s_cmp_lt_u32 s88, s87
	v_permlane32_swap_b32_e32 v8, v4
	v_max_f32_e32 v178, v8, v4
	s_cbranch_scc0 .LBB0_443
.LBB0_436:
	v_cmp_lt_f32_e32 vcc, s67, v178
	s_cbranch_vccz .LBB0_440
	v_max_f32_e32 v126, v178, v178
	v_max_f32_e32 v126, 0, v126
	v_exp_f32_e64 v127, -v126
	s_and_saveexec_b64 s[58:59], s[6:7]
	ds_write_b32 v16, v127
	s_or_b64 exec, exec, s[58:59]
	s_waitcnt lgkmcnt(0)
	v_add_u32_e32 v140, s76, v2
	ds_read_b128 v[128:131], v140 offset:64
	ds_read_b128 v[132:135], v140 offset:96
	ds_read_b128 v[136:139], v140
	ds_read_b128 v[140:143], v140 offset:32
	v_add_f32_e32 v247, v247, v126
	v_sub_f32_e32 v146, v146, v126
	v_sub_f32_e32 v147, v147, v126
	v_sub_f32_e32 v148, v148, v126
	v_sub_f32_e32 v149, v149, v126
	v_sub_f32_e32 v150, v150, v126
	v_sub_f32_e32 v151, v151, v126
	v_sub_f32_e32 v152, v152, v126
	v_sub_f32_e32 v153, v153, v126
	v_sub_f32_e32 v154, v154, v126
	v_sub_f32_e32 v155, v155, v126
	v_sub_f32_e32 v156, v156, v126
	v_sub_f32_e32 v157, v157, v126
	v_sub_f32_e32 v158, v158, v126
	v_sub_f32_e32 v159, v159, v126
	v_sub_f32_e32 v160, v160, v126
	v_sub_f32_e32 v161, v161, v126
	v_sub_f32_e32 v82, v82, v126
	v_sub_f32_e32 v83, v83, v126
	v_sub_f32_e32 v84, v84, v126
	v_sub_f32_e32 v85, v85, v126
	v_sub_f32_e32 v86, v86, v126
	v_sub_f32_e32 v87, v87, v126
	v_sub_f32_e32 v88, v88, v126
	v_sub_f32_e32 v89, v89, v126
	v_sub_f32_e32 v90, v90, v126
	v_sub_f32_e32 v91, v91, v126
	v_sub_f32_e32 v92, v92, v126
	v_sub_f32_e32 v93, v93, v126
	v_sub_f32_e32 v94, v94, v126
	v_sub_f32_e32 v95, v95, v126
	v_sub_f32_e32 v96, v96, v126
	v_sub_f32_e32 v97, v97, v126
	v_sub_f32_e32 v98, v98, v126
	v_sub_f32_e32 v99, v99, v126
	v_sub_f32_e32 v100, v100, v126
	v_sub_f32_e32 v101, v101, v126
	v_sub_f32_e32 v102, v102, v126
	v_sub_f32_e32 v103, v103, v126
	v_sub_f32_e32 v104, v104, v126
	v_sub_f32_e32 v105, v105, v126
	v_sub_f32_e32 v106, v106, v126
	v_sub_f32_e32 v107, v107, v126
	v_sub_f32_e32 v108, v108, v126
	v_sub_f32_e32 v109, v109, v126
	v_sub_f32_e32 v110, v110, v126
	v_sub_f32_e32 v111, v111, v126
	v_sub_f32_e32 v112, v112, v126
	v_sub_f32_e32 v113, v113, v126
	v_mul_f32_e32 v251, v251, v127
	s_waitcnt lgkmcnt(2)
	v_pk_mul_f32 v[30:31], v[30:31], v[132:133]
	v_pk_mul_f32 v[26:27], v[26:27], v[128:129]
	s_waitcnt lgkmcnt(0)
	v_pk_mul_f32 v[22:23], v[22:23], v[140:141]
	v_pk_mul_f32 v[32:33], v[32:33], v[134:135]
	v_pk_mul_f32 v[28:29], v[28:29], v[130:131]
	v_pk_mul_f32 v[24:25], v[24:25], v[142:143]
	v_pk_mul_f32 v[20:21], v[20:21], v[138:139]
	v_pk_mul_f32 v[18:19], v[18:19], v[136:137]
	v_pk_mul_f32 v[46:47], v[46:47], v[132:133]
	v_pk_mul_f32 v[42:43], v[42:43], v[128:129]
	v_pk_mul_f32 v[38:39], v[38:39], v[140:141]
	v_pk_mul_f32 v[48:49], v[48:49], v[134:135]
	v_pk_mul_f32 v[44:45], v[44:45], v[130:131]
	v_pk_mul_f32 v[40:41], v[40:41], v[142:143]
	v_pk_mul_f32 v[36:37], v[36:37], v[138:139]
	v_pk_mul_f32 v[34:35], v[34:35], v[136:137]
	v_pk_mul_f32 v[62:63], v[62:63], v[132:133]
	v_pk_mul_f32 v[58:59], v[58:59], v[128:129]
	v_pk_mul_f32 v[54:55], v[54:55], v[140:141]
	v_pk_mul_f32 v[64:65], v[64:65], v[134:135]
	v_pk_mul_f32 v[60:61], v[60:61], v[130:131]
	v_pk_mul_f32 v[56:57], v[56:57], v[142:143]
	v_pk_mul_f32 v[52:53], v[52:53], v[138:139]
	v_pk_mul_f32 v[50:51], v[50:51], v[136:137]
	v_pk_mul_f32 v[78:79], v[78:79], v[132:133]
	v_pk_mul_f32 v[74:75], v[74:75], v[128:129]
	v_pk_mul_f32 v[70:71], v[70:71], v[140:141]
	v_pk_mul_f32 v[80:81], v[80:81], v[134:135]
	v_pk_mul_f32 v[76:77], v[76:77], v[130:131]
	v_pk_mul_f32 v[72:73], v[72:73], v[142:143]
	v_pk_mul_f32 v[68:69], v[68:69], v[138:139]
	v_pk_mul_f32 v[66:67], v[66:67], v[136:137]
; #define SB() __builtin_amdgcn_sched_barrier(0)
; #define MF32(a,b,c) __builtin_amdgcn_mfma_f32_32x32x16_bf16(a,b,c,0,0,0)
; #define EXP1(x) x=__builtin_amdgcn_exp2f((x)-mh_)
; __device__ __forceinline__ bf16x8 vfrag(lds_cptr vp,int i){ const s16x4 lo=vtr(vp+(i&3)*4096+(i>>2)*1024), hh=vtr(vp+(i&3)*4096+(i>>2)*1024+512); return (bf16x8){lo[0],lo[1],lo[2],lo[3],hh[0],hh[1],hh[2],hh[3]}; }
; __device__ __forceinline__ u32x4 packw(const f32x16&p,int base){ u32x4 w; w[0]=cvtpk_s(p[base],p[base+1]); w[1]=cvtpk_s(p[base+2],p[base+3]); w[2]=cvtpk_s(p[base+4],p[base+5]); w[3]=cvtpk_s(p[base+6],p[base+7]); return w; }
;   #define KF(i) LDSQ(kpn+((i)>>1)*2048+((i)&1)*512)
;   #define QF(d0) LDSQ(qp+(d0)*1024)
; template<int THRL,bool FIRST> __device__ __forceinline__ void step_main(f32x16&p0,f32x16&p1,f32x16&n0,f32x16&n1,St&S,lds_cptr kpn,lds_cptr qp,lds_cptr vp,float*wsf,int r32,int hi,float&rm){
;     ...
;   bf16x8 ka=KF(0),kb=KF(1),kc=KF(2),kd=KF(3),qa=QF(0),qb=QF(1);
;   decide<THRL,FIRST>(rm,S,wsf,r32,hi);
;   u32x4 pw0,pw1,pw2,pw3; const float mh_=S.mhat; const f32x16 z=f32x16{};
;   SB();
;   n0=MF32(ka,qa,z); ka=KF(4); EXP1(p0[0]);EXP1(p0[1]);EXP1(p0[2]); SB();
;   n1=MF32(kb,qa,z); kb=KF(5); qa=QF(2); EXP1(p0[3]);EXP1(p0[4]);EXP1(p0[5]); SB();
;   n0=MF32(kc,qb,n0);   kc=KF(6); EXP1(p0[6]);EXP1(p0[7]);EXP1(p0[8]); SB();
;   n1=MF32(kd,qb,n1);   kd=KF(7); qb=QF(3); EXP1(p0[9]);EXP1(p0[10]);EXP1(p0[11]); SB();
;   bf16x8 vfa=vfrag(vp,0);
;   n0=MF32(ka,qa,n0);   EXP1(p0[12]);EXP1(p0[13]);EXP1(p0[14]); pw0=packw(p0,0); SB();
;   bf16x8 vfb=vfrag(vp,1);
;   n1=MF32(kb,qa,n1);   EXP1(p0[15]);EXP1(p1[0]);EXP1(p1[1]); SB();
;   bf16x8 vfc=vfrag(vp,2);
;   n0=MF32(kc,qb,n0);   EXP1(p1[2]);EXP1(p1[3]);EXP1(p1[4]); pw1=packw(p0,8); SB();
;   bf16x8 vfd=vfrag(vp,3);
;   n1=MF32(kd,qb,n1);   EXP1(p1[5]);EXP1(p1[6]);EXP1(p1[7]); SB();
;     ...
;   float sa=p0[0]+p0[1];
;     ...
;   PVG(0,pw0,vfa,4, p0[2],p0[3],p0[4],p0[5],   do{EXP1(p1[8]);EXP1(p1[9]);}while(0));
;   PVG(1,pw0,vfb,5, p0[6],p0[7],p0[8],p0[9], do{EXP1(p1[10]);EXP1(p1[11]);}while(0));
;   PVG(2,pw0,vfc,6, p0[10],p0[11],p0[12],p0[13], do{EXP1(p1[12]);EXP1(p1[13]);}while(0));
;   PVG(3,pw0,vfd,7, p0[14],p0[15],p1[0],p1[1],   do{EXP1(p1[14]);EXP1(p1[15]);}while(0));
;   PVG(4,pw1,vfa,8, p1[2],p1[3],p1[4],p1[5],   pw2=packw(p1,0));
;   PVG(5,pw1,vfb,9, p1[6],p1[7],p1[8],p1[9], pw3=packw(p1,8));
.LBB0_440:
	s_add_i32 s4, s86, 0x2000
	s_cmpk_lg_i32 s86, 0x4000
	s_cselect_b32 s89, s4, 0
	v_mfma_f32_32x32x16_bf16 v[130:145], v[204:207], v[164:167], v[146:161]
	s_add_i32 s4, s89, s80
	s_mov_b32 s5, m0
	s_mov_b32 m0, s4
	s_nop 0
	global_load_lds_dwordx4 v252, s[50:51]
	s_mov_b32 m0, s5
	v_exp_f32_e32 v190, v98
	v_exp_f32_e32 v191, v99
	v_exp_f32_e32 v192, v100
	v_mfma_f32_32x32x16_bf16 v[114:129], v[208:211], v[164:167], v[146:161]
	s_mov_b32 s4, m0
	s_mov_b32 m0, s77
	s_nop 0
	global_load_lds_dwordx4 v250, s[48:49]
	s_mov_b32 m0, s4
	v_exp_f32_e32 v193, v101
	v_exp_f32_e32 v194, v102
	v_exp_f32_e32 v195, v103
	v_mfma_f32_32x32x16_bf16 v[130:145], v[212:215], v[168:171], v[130:145]
	s_add_u32 s58, s48, 0x80
	s_addc_u32 s59, s49, 0
	s_mov_b32 s4, m0
	s_mov_b32 m0, s39
	s_nop 0
	global_load_lds_dwordx4 v250, s[58:59]
	s_mov_b32 m0, s4
	v_exp_f32_e32 v196, v104
	v_exp_f32_e32 v197, v105
	v_exp_f32_e32 v198, v106
	v_mfma_f32_32x32x16_bf16 v[114:129], v[216:219], v[168:171], v[114:129]
	v_exp_f32_e32 v17, v107
	v_exp_f32_e32 v199, v108
	v_exp_f32_e32 v200, v109
	v_mfma_f32_32x32x16_bf16 v[130:145], v[220:223], v[172:175], v[130:145]
	v_exp_f32_e32 v201, v110
	ds_read_b64_tr_b16 v[4:5], v246 offset:24576
	ds_read_b64_tr_b16 v[6:7], v246 offset:25088
	v_exp_f32_e32 v202, v111
	v_exp_f32_e32 v178, v112
	v_cvt_pk_bf16_f32 v8, v190, v191
	v_cvt_pk_bf16_f32 v9, v192, v193
	v_cvt_pk_bf16_f32 v10, v194, v195
	v_cvt_pk_bf16_f32 v11, v196, v197
	v_mfma_f32_32x32x16_bf16 v[114:129], v[224:227], v[172:175], v[114:129]
	ds_read_b64_tr_b16 v[106:107], v246 offset:28672
	ds_read_b64_tr_b16 v[108:109], v246 offset:29184
	v_exp_f32_e32 v180, v82
	v_exp_f32_e32 v179, v113
	v_exp_f32_e32 v181, v83
	v_mfma_f32_32x32x16_bf16 v[130:145], v[228:231], v[236:239], v[130:145]
	ds_read_b64_tr_b16 v[110:111], v246 offset:32768
	ds_read_b64_tr_b16 v[112:113], v246 offset:33280
	v_exp_f32_e32 v182, v84
	v_exp_f32_e32 v183, v85
	v_exp_f32_e32 v184, v86
	v_cvt_pk_bf16_f32 v82, v198, v17
	v_cvt_pk_bf16_f32 v83, v199, v200
	v_cvt_pk_bf16_f32 v84, v201, v202
	v_cvt_pk_bf16_f32 v85, v178, v179
	v_mfma_f32_32x32x16_bf16 v[114:129], v[232:235], v[236:239], v[114:129]
	v_add_u32_e32 v240, s86, v249
	ds_read_b64_tr_b16 v[98:99], v246 offset:36864
	ds_read_b64_tr_b16 v[100:101], v246 offset:37376
	v_exp_f32_e32 v185, v87
	v_exp_f32_e32 v186, v88
	v_exp_f32_e32 v187, v89
	s_waitcnt lgkmcnt(6)
	v_mfma_f32_32x32x16_bf16 v[18:33], v[8:11], v[4:7], v[18:33]
	ds_read_b128 v[204:207], v240
	v_add_f32_e32 v86, v190, v191
	ds_read_b64_tr_b16 v[12:13], v246 offset:25600
	ds_read_b64_tr_b16 v[14:15], v246 offset:26112
	v_add_f32_e32 v86, v192, v86
	v_exp_f32_e32 v103, v91
	v_add_f32_e32 v4, v193, v86
	v_add_f32_e32 v4, v194, v4
	v_add_f32_e32 v86, v195, v4
	v_exp_f32_e32 v102, v90
	s_waitcnt lgkmcnt(7)
	v_mfma_f32_32x32x16_bf16 v[34:49], v[8:11], v[106:109], v[34:49]
	ds_read_b64_tr_b16 v[4:5], v246 offset:29696
	ds_read_b64_tr_b16 v[6:7], v246 offset:30208
	ds_read_b128 v[208:211], v240 offset:512
	v_add_f32_e32 v86, v196, v86
	v_add_f32_e32 v86, v197, v86
	v_add_f32_e32 v86, v198, v86
	v_exp_f32_e32 v104, v92
	v_add_f32_e32 v17, v17, v86
	v_exp_f32_e32 v105, v93
	s_waitcnt lgkmcnt(8)
	v_mfma_f32_32x32x16_bf16 v[50:65], v[8:11], v[110:113], v[50:65]
	ds_read_b64_tr_b16 v[86:87], v246 offset:33792
	ds_read_b64_tr_b16 v[88:89], v246 offset:34304
	ds_read_b128 v[212:215], v240 offset:2048
	v_add_f32_e32 v17, v199, v17
	v_add_f32_e32 v17, v200, v17
	v_add_f32_e32 v17, v201, v17
	v_exp_f32_e32 v106, v94
	v_add_f32_e32 v17, v202, v17
	v_exp_f32_e32 v107, v95
	s_waitcnt lgkmcnt(9)
	v_mfma_f32_32x32x16_bf16 v[66:81], v[8:11], v[98:101], v[66:81]
	ds_read_b64_tr_b16 v[90:91], v246 offset:37888
	ds_read_b64_tr_b16 v[92:93], v246 offset:38400
	ds_read_b128 v[216:219], v240 offset:2560
	v_add_f32_e32 v17, v178, v17
	v_add_f32_e32 v8, v179, v17
	v_add_f32_e32 v8, v180, v8
	v_exp_f32_e32 v108, v96
	v_add_f32_e32 v17, v181, v8
	v_exp_f32_e32 v109, v97
	s_waitcnt lgkmcnt(9)
; __device__ __forceinline__ float max3f(float a,float b,float c){float r;asm("v_max3_f32 %0, %1, %2, %3":"=v"(r):"v"(a),"v"(b),"v"(c));return r;}
; __device__ __forceinline__ float max2f(float a,float b){float r;asm("v_max_f32_e32 %0, %1, %2":"=v"(r):"v"(a),"v"(b));return r;}
;   #define PVG(i,PW,VF,NEXTI,X0,X1,Y0,Y1,EXTRA) do{ S.o[(i)&3]=MF32(__builtin_bit_cast(bf16x8,PW),VF,S.o[(i)&3]); if((NEXTI)<16){ VF=vfrag(vp,(NEXTI)<16?(NEXTI):0); } sa+=X0; sa+=X1; sa+=Y0; sa+=Y1; EXTRA; SB(); }while(0)
;   #define PINAB() asm volatile("":"+v"(ma),"+v"(mb))
; template<int THRL,bool FIRST> __device__ __forceinline__ void step_main(f32x16&p0,f32x16&p1,f32x16&n0,f32x16&n1,St&S,lds_cptr kpn,lds_cptr qp,lds_cptr vp,float*wsf,int r32,int hi,float&rm){
;     ...
;   PVG(7,pw1,vfd,11, p1[14],p1[15],0.f,0.f, do{}while(0));
;   float ma,mb;
;     ...
;   PVG(8,pw2,vfa,12,0.f,0.f,0.f,0.f, do{ma=max3f(n0[0],n0[1],n1[0]);mb=max3f(n0[2],n0[3],n1[1]);PINAB();}while(0));
;   PVG(9,pw2,vfb,13,0.f,0.f,0.f,0.f, do{ma=max3f(ma,n1[2],n1[3]);mb=max3f(mb,n0[4],n0[5]);PINAB();}while(0));
;   PVG(10,pw2,vfc,14,0.f,0.f,0.f,0.f, do{ma=max3f(ma,n0[6],n0[7]);mb=max3f(mb,n1[4],n1[5]);PINAB();}while(0));
;   PVG(11,pw2,vfd,15,0.f,0.f,0.f,0.f, do{ma=max3f(ma,n1[6],n1[7]);mb=max3f(mb,n0[8],n0[9]);PINAB();}while(0));
;   PVG(12,pw3,vfa,16,0.f,0.f,0.f,0.f, do{ma=max3f(ma,n0[10],n0[11]);mb=max3f(mb,n1[8],n1[9]);PINAB();}while(0));
;   PVG(13,pw3,vfb,16,0.f,0.f,0.f,0.f, do{ma=max3f(ma,n1[10],n1[11]);mb=max3f(mb,n0[12],n0[13]);PINAB();}while(0));
;   PVG(14,pw3,vfc,16,0.f,0.f,0.f,0.f, do{ma=max3f(ma,n0[14],n0[15]);mb=max3f(mb,n1[12],n1[13]);PINAB();}while(0));
;   PVG(15,pw3,vfd,16,0.f,0.f,0.f,0.f, do{ma=max3f(ma,n1[14],n1[15]);ma=max2f(ma,mb);PINAB();}while(0));
;     ...
;   { auto rr=__builtin_amdgcn_permlane32_swap(__float_as_uint(ma),__float_as_uint(ma),false,false); rm=max2f(__uint_as_float(rr[0]),__uint_as_float(rr[1])); }
	v_mfma_f32_32x32x16_bf16 v[18:33], v[82:85], v[12:15], v[18:33]
	ds_read_b64_tr_b16 v[8:9], v246 offset:26624
	ds_read_b64_tr_b16 v[10:11], v246 offset:27136
	ds_read_b128 v[220:223], v240 offset:4096
	v_add_f32_e32 v17, v182, v17
	v_add_f32_e32 v17, v183, v17
	v_add_f32_e32 v17, v184, v17
	v_add_f32_e32 v17, v185, v17
	v_cvt_pk_bf16_f32 v12, v180, v181
	v_cvt_pk_bf16_f32 v13, v182, v183
	v_cvt_pk_bf16_f32 v14, v184, v185
	v_cvt_pk_bf16_f32 v15, v186, v187
	s_waitcnt lgkmcnt(10)
	v_mfma_f32_32x32x16_bf16 v[34:49], v[82:85], v[4:7], v[34:49]
	ds_read_b64_tr_b16 v[94:95], v246 offset:30720
	ds_read_b64_tr_b16 v[96:97], v246 offset:31232
	ds_read_b128 v[224:227], v240 offset:4608
	v_add_f32_e32 v17, v186, v17
	v_add_f32_e32 v17, v187, v17
	v_add_f32_e32 v17, v102, v17
	v_add_f32_e32 v17, v103, v17
	v_cvt_pk_bf16_f32 v4, v102, v103
	v_cvt_pk_bf16_f32 v5, v104, v105
	v_cvt_pk_bf16_f32 v6, v106, v107
	v_cvt_pk_bf16_f32 v7, v108, v109
	s_waitcnt lgkmcnt(10)
	v_mfma_f32_32x32x16_bf16 v[50:65], v[82:85], v[86:89], v[50:65]
	ds_read_b64_tr_b16 v[98:99], v246 offset:34816
	ds_read_b64_tr_b16 v[100:101], v246 offset:35328
	ds_read_b128 v[228:231], v240 offset:6144
	v_add_f32_e32 v17, v104, v17
	v_add_f32_e32 v17, v105, v17
	v_add_f32_e32 v17, v106, v17
	v_add_f32_e32 v17, v107, v17
	s_waitcnt lgkmcnt(10)
	v_mfma_f32_32x32x16_bf16 v[66:81], v[82:85], v[90:93], v[66:81]
	ds_read_b64_tr_b16 v[86:87], v246 offset:38912
	ds_read_b64_tr_b16 v[88:89], v246 offset:39424
	ds_read_b128 v[232:235], v240 offset:6656
	v_add_f32_e32 v17, v108, v17
	v_add_f32_e32 v17, v109, v17
	s_waitcnt lgkmcnt(10)
	v_mfma_f32_32x32x16_bf16 v[18:33], v[12:15], v[8:11], v[18:33]
	ds_read_b64_tr_b16 v[82:83], v246 offset:27648
	ds_read_b64_tr_b16 v[84:85], v246 offset:28160
	v_max3_f32 v90, v130, v131, v114
	v_max3_f32 v91, v132, v133, v115
	s_nop 0
	s_waitcnt lgkmcnt(9)
	v_mfma_f32_32x32x16_bf16 v[34:49], v[12:15], v[94:97], v[34:49]
	ds_read_b64_tr_b16 v[8:9], v246 offset:31744
	ds_read_b64_tr_b16 v[10:11], v246 offset:32256
	v_max3_f32 v102, v90, v116, v117
	v_max3_f32 v103, v91, v134, v135
	s_nop 0
	s_waitcnt lgkmcnt(8)
	v_mfma_f32_32x32x16_bf16 v[50:65], v[12:15], v[98:101], v[50:65]
	ds_read_b64_tr_b16 v[90:91], v246 offset:35840
	ds_read_b64_tr_b16 v[92:93], v246 offset:36352
	v_max3_f32 v102, v102, v136, v137
	v_max3_f32 v103, v103, v118, v119
	s_nop 0
	s_waitcnt lgkmcnt(7)
	v_mfma_f32_32x32x16_bf16 v[66:81], v[12:15], v[86:89], v[66:81]
	ds_read_b64_tr_b16 v[94:95], v246 offset:39936
	ds_read_b64_tr_b16 v[96:97], v246 offset:40448
	v_max3_f32 v98, v102, v120, v121
	v_max3_f32 v99, v103, v138, v139
	s_nop 0
	s_waitcnt lgkmcnt(6)
	v_mfma_f32_32x32x16_bf16 v[18:33], v[4:7], v[82:85], v[18:33]
	v_max3_f32 v12, v98, v140, v141
	v_max3_f32 v13, v99, v122, v123
	s_nop 0
	s_waitcnt lgkmcnt(4)
	v_mfma_f32_32x32x16_bf16 v[34:49], v[4:7], v[8:11], v[34:49]
	v_max3_f32 v12, v12, v124, v125
	v_max3_f32 v13, v13, v142, v143
	s_nop 0
	s_waitcnt lgkmcnt(2)
	v_mfma_f32_32x32x16_bf16 v[50:65], v[4:7], v[90:93], v[50:65]
	v_max3_f32 v8, v12, v144, v145
	v_max3_f32 v9, v13, v126, v127
	s_nop 0
	s_waitcnt lgkmcnt(0)
	v_mfma_f32_32x32x16_bf16 v[66:81], v[4:7], v[94:97], v[66:81]
	v_max3_f32 v8, v8, v128, v129
	s_nop 0
	v_max_f32_e32 v8, v8, v9
	s_nop 0
	v_mov_b32_e32 v163, v8
	s_waitcnt vmcnt(0) lgkmcnt(0)
	s_barrier
	v_permlane32_swap_b32_e32 v8, v163
	v_max_f32_e32 v94, v8, v163
	v_add_f32_e32 v17, v251, v17
	v_cmp_lt_f32_e32 vcc, s67, v94
	s_cbranch_vccz .LBB0_435
	v_max_f32_e32 v94, v94, v94
	v_max_f32_e32 v94, 0, v94
	v_exp_f32_e64 v95, -v94
	s_and_saveexec_b64 s[58:59], s[6:7]
	s_cbranch_execz .LBB0_434
	ds_write_b32 v16, v95
	s_branch .LBB0_434
